# prologue: weight transposes dealt to workgroups 96..255 only (workgroups 0..95 carry the adaLN modulation items), balancing phase 0
# speedup vs baseline: 1.0113x; 1.0113x over previous
; #define LAS __attribute__((address_space(3)))
; __device__ __forceinline__ void phase_prologue(const Params& p, LAS unsigned char* lds, int G, int tid, int wave, int lane) {
;     ...
;     LAS float* scr = (LAS float*)(lds + wave * 16384);
;     const int gw = blockIdx.x * NWAVES + wave, NGW = G * NWAVES;
;     constexpr int I_IN = 16 * 64, I_O = 8 * 32, I_1 = 16 * 128, I_2 = 64 * 32, I_L = I_IN + I_O + I_1 + I_2;
;     for (int it = gw; it < DEPTH * I_L; it += NGW) {
;         const int l = it / I_L; int r = it % I_L;
.LBB0_401:
	v_readlane_b32 s0, v254, 22
	s_add_i32 s10, s87, s0
	s_mov_b32 s32, s52
	s_cmpk_lg_u32 s52, 0x800
	s_cbranch_scc1 .Ltr_std
	s_cmpk_lt_i32 s10, 0x300
	s_cbranch_scc1 .LBB0_424
	s_sub_i32 s10, s10, 0x300
	s_movk_i32 s32, 0x500
.Ltr_std:
	s_cmpk_gt_i32 s10, 0x53ff
	s_cbranch_scc1 .LBB0_424
	v_readlane_b32 s12, v254, 58
	v_readlane_b32 s16, v254, 62
	v_readlane_b32 s17, v254, 63
	s_add_u32 s11, s16, s92
	v_readlane_b32 s13, v254, 59
	v_readlane_b32 s26, v255, 8
	s_addc_u32 s12, s17, s93
	v_readlane_b32 s14, v254, 60
	v_readlane_b32 s27, v255, 9
	s_add_u32 s13, s26, s92
	v_readlane_b32 s15, v254, 61
	s_addc_u32 s14, s27, s93
	v_readlane_b32 s4, v254, 38
	v_readlane_b32 s5, v254, 39
	s_add_u32 s15, s4, s92
	s_addc_u32 s16, s5, s93
	s_lshl_b32 s0, s87, 14
	s_add_i32 s0, s0, 0
	v_readlane_b32 s18, v255, 0
	s_add_u32 s17, s73, 0x4400000
	v_readlane_b32 s19, v255, 1
	s_addc_u32 s18, s57, 0
	v_readlane_b32 s20, v255, 2
	v_lshlrev_b32_e32 v1, 3, v168
	s_add_u32 s19, s73, 0x2400000
	v_readlane_b32 s21, v255, 3
	v_lshrrev_b32_e32 v5, 3, v168
	v_and_b32_e32 v6, 56, v1
	s_addc_u32 s20, s57, 0
	v_readlane_b32 s22, v255, 4
	v_lshrrev_b32_e32 v0, 5, v168
	v_and_b32_e32 v2, 31, v166
	v_mul_u32_u24_e32 v1, 0x84, v6
	v_lshlrev_b32_e32 v3, 2, v5
	s_add_u32 s21, s73, 0xc00000
	v_lshl_add_u32 v4, v2, 2, s0
	v_add3_u32 v7, s0, v1, v3
	v_or_b32_e32 v11, 8, v5
	v_or_b32_e32 v12, 16, v5
	v_or_b32_e32 v13, 24, v5
	s_addc_u32 s22, s57, 0
	v_mov_b32_e32 v1, v0
	v_readlane_b32 s23, v255, 5
	v_readlane_b32 s24, v255, 6
	v_readlane_b32 s25, v255, 7
	v_readlane_b32 s6, v254, 40
	v_readlane_b32 s7, v254, 41
	s_branch .LBB0_404
.LBB0_403:
	s_add_i32 s10, s10, s32
	s_cmpk_gt_i32 s10, 0x53ff
	s_cbranch_scc1 .LBB0_424
